# rare path scales l itself (common path adds only); second V staging write reuses first address
# speedup vs baseline: 1.0070x; 1.0017x over previous
; __device__ __forceinline__ int crow(int r, int hi) { return (r & 3) + 8 * (r >> 2) + 4 * hi; }
; #define SWRITE(ts, v3) do { const int kb_ = ((ts) & 1) * SHM_K, rb_ = ((ts) & 1) * SHM_R, vb_ = (v3) * SHM_V; \
;         *(LAS bf16x8*)(lds + kb_ + kws) = st_k0; *(LAS bf16x8*)(lds + kb_ + kws + 32 * 256) = st_k1; \
;         *(LAS bf16x8*)(lds + vb_ + vst0) = st_v0; *(LAS bf16x8*)(lds + vb_ + vst1) = st_v1; *(LAS bf16x8*)(lds + rb_ + rws) = st_r; } while (0)
; __device__ __forceinline__ void attn_block(const Ptrs& P, int b, int h, int qb, LAS char* lds) {
;     ...
; #pragma unroll
;         for (int r = 0; r < 16; ++r) { p0[r] = __builtin_amdgcn_exp2f(p0[r] - m_reg); p1[r] = __builtin_amdgcn_exp2f(p1[r] - m_reg); }
;         float ps = 0.f;
; #pragma unroll
;         for (int r = 0; r < 16; ++r) ps += p0[r];
; #pragma unroll
;         for (int r = 0; r < 16; ++r) ps += p1[r];
;         { auto sw_ = __builtin_amdgcn_permlane32_swap(__float_as_uint(ps), __float_as_uint(ps), false, false); ps = __uint_as_float(sw_[0]) + __uint_as_float(sw_[1]); }
;         l_reg = l_reg * alpha + ps;
;         PK4(p0, 0, pa0); PK4(p0, 8, pa1); PK4(p1, 0, pa2); PK4(p1, 8, pa3);
;         if (__any(alpha < 1.f)) { if (hi == 0) al_l[r32] = alpha; asm volatile("s_waitcnt lgkmcnt(0)" ::: "memory");
; #pragma unroll
;             for (int d_ = 0; d_ < 4; ++d_)
; #pragma unroll
;                 for (int r = 0; r < 16; ++r) o[d_][r] *= al_l[crow(r, hi)]; }
;         if (ts < NT) SWRITE(ts, ts3);
.Lattn_fast:
.Lattn_exp:
	v_exp_f32_e32 v84, v84
	v_exp_f32_e32 v85, v85
	v_exp_f32_e32 v86, v86
	v_exp_f32_e32 v87, v87
	v_exp_f32_e32 v88, v88
	v_exp_f32_e32 v89, v89
	v_exp_f32_e32 v90, v90
	v_exp_f32_e32 v91, v91
	v_exp_f32_e32 v92, v92
	v_exp_f32_e32 v93, v93
	v_exp_f32_e32 v94, v94
	v_exp_f32_e32 v95, v95
	v_exp_f32_e32 v96, v96
	v_exp_f32_e32 v97, v97
	v_exp_f32_e32 v98, v98
	v_exp_f32_e32 v99, v99
	v_exp_f32_e32 v68, v68
	v_add_f32_e32 v199, v84, v85
	v_exp_f32_e32 v69, v69
	v_add_f32_e32 v201, v86, v87
	v_exp_f32_e32 v70, v70
	v_add_f32_e32 v202, v88, v89
	v_exp_f32_e32 v71, v71
	v_add_f32_e32 v203, v90, v91
	v_exp_f32_e32 v72, v72
	v_add_f32_e32 v199, v92, v199
	v_exp_f32_e32 v73, v73
	v_add_f32_e32 v201, v93, v201
	v_exp_f32_e32 v74, v74
	v_add_f32_e32 v202, v94, v202
	v_exp_f32_e32 v75, v75
	v_add_f32_e32 v203, v95, v203
	v_exp_f32_e32 v76, v76
	v_add_f32_e32 v199, v96, v199
	v_exp_f32_e32 v77, v77
	v_add_f32_e32 v201, v97, v201
	v_exp_f32_e32 v78, v78
	v_add_f32_e32 v202, v98, v202
	v_exp_f32_e32 v79, v79
	v_add_f32_e32 v203, v99, v203
	v_exp_f32_e32 v80, v80
	v_exp_f32_e32 v81, v81
	v_exp_f32_e32 v82, v82
	v_exp_f32_e32 v83, v83
	v_add_f32_e32 v199, v68, v199
	v_add_f32_e32 v201, v69, v201
	v_add_f32_e32 v202, v70, v202
	v_add_f32_e32 v203, v71, v203
	v_add_f32_e32 v199, v72, v199
	v_add_f32_e32 v201, v73, v201
	v_add_f32_e32 v202, v74, v202
	v_add_f32_e32 v203, v75, v203
	v_add_f32_e32 v199, v76, v199
	v_add_f32_e32 v201, v77, v201
	v_add_f32_e32 v202, v78, v202
	v_add_f32_e32 v203, v79, v203
	v_add_f32_e32 v199, v80, v199
	v_add_f32_e32 v201, v81, v201
	v_add_f32_e32 v202, v82, v202
	v_add_f32_e32 v203, v83, v203
	v_add_f32_e32 v199, v199, v201
	v_add_f32_e32 v202, v202, v203
	v_cvt_pk_bf16_f32 v83, v82, v83
	v_cvt_pk_bf16_f32 v82, v80, v81
	v_cvt_pk_bf16_f32 v81, v78, v79
	v_cvt_pk_bf16_f32 v80, v76, v77
	v_cvt_pk_bf16_f32 v76, v68, v69
	v_cvt_pk_bf16_f32 v77, v70, v71
	v_cvt_pk_bf16_f32 v78, v72, v73
	v_cvt_pk_bf16_f32 v79, v74, v75
	v_cvt_pk_bf16_f32 v68, v84, v85
	v_cvt_pk_bf16_f32 v69, v86, v87
	v_cvt_pk_bf16_f32 v70, v88, v89
	v_cvt_pk_bf16_f32 v71, v90, v91
	v_add_f32_e32 v85, v199, v202
	v_cvt_pk_bf16_f32 v72, v92, v93
	v_cvt_pk_bf16_f32 v73, v94, v95
	v_cvt_pk_bf16_f32 v74, v96, v97
	v_cvt_pk_bf16_f32 v75, v98, v99
	s_cmp_eq_u64 s[22:23], exec
	s_cbranch_scc1 .LBB0_623
	v_mov_b32_e32 v84, v200
	s_and_saveexec_b64 s[22:23], s[0:1]
	ds_write_b32 v194, v84 offset:128
	s_or_b64 exec, exec, s[22:23]
	s_waitcnt lgkmcnt(0)
	ds_read_b128 v[88:91], v193 offset:224
	ds_read_b128 v[92:95], v193 offset:192
	ds_read_b128 v[96:99], v193 offset:160
	ds_read_b128 v[200:203], v193 offset:128
	s_waitcnt lgkmcnt(3)
	v_pk_mul_f32 v[66:67], v[66:67], v[90:91]
	s_waitcnt lgkmcnt(2)
	v_pk_mul_f32 v[62:63], v[62:63], v[94:95]
	s_waitcnt lgkmcnt(1)
	v_pk_mul_f32 v[58:59], v[58:59], v[98:99]
	s_waitcnt lgkmcnt(0)
	v_pk_mul_f32 v[54:55], v[54:55], v[202:203]
	v_pk_mul_f32 v[64:65], v[64:65], v[88:89]
	v_pk_mul_f32 v[60:61], v[60:61], v[92:93]
	v_pk_mul_f32 v[56:57], v[56:57], v[96:97]
	v_pk_mul_f32 v[52:53], v[52:53], v[200:201]
	v_pk_mul_f32 v[50:51], v[50:51], v[90:91]
	v_pk_mul_f32 v[46:47], v[46:47], v[94:95]
	v_pk_mul_f32 v[42:43], v[42:43], v[98:99]
	v_pk_mul_f32 v[38:39], v[38:39], v[202:203]
	v_pk_mul_f32 v[48:49], v[48:49], v[88:89]
	v_pk_mul_f32 v[44:45], v[44:45], v[92:93]
	v_pk_mul_f32 v[40:41], v[40:41], v[96:97]
	v_pk_mul_f32 v[36:37], v[36:37], v[200:201]
	v_pk_mul_f32 v[34:35], v[34:35], v[90:91]
	v_pk_mul_f32 v[30:31], v[30:31], v[94:95]
	v_pk_mul_f32 v[26:27], v[26:27], v[98:99]
	v_pk_mul_f32 v[22:23], v[22:23], v[202:203]
	v_pk_mul_f32 v[32:33], v[32:33], v[88:89]
	v_pk_mul_f32 v[28:29], v[28:29], v[92:93]
	v_pk_mul_f32 v[24:25], v[24:25], v[96:97]
	v_pk_mul_f32 v[20:21], v[20:21], v[200:201]
	v_pk_mul_f32 v[18:19], v[18:19], v[90:91]
	v_pk_mul_f32 v[14:15], v[14:15], v[94:95]
	v_pk_mul_f32 v[10:11], v[10:11], v[98:99]
	v_pk_mul_f32 v[6:7], v[6:7], v[202:203]
	v_pk_mul_f32 v[16:17], v[16:17], v[88:89]
	v_pk_mul_f32 v[12:13], v[12:13], v[92:93]
	v_pk_mul_f32 v[8:9], v[8:9], v[96:97]
	v_pk_mul_f32 v[4:5], v[4:5], v[200:201]
	v_mul_f32_e32 v198, v198, v84
.LBB0_623:
	s_cmp_gt_u32 s77, s76
	s_cbranch_scc1 .LBB0_625
	s_and_b32 s22, s77, 1
	s_lshl_b32 s23, s38, 14
	v_lshl_add_u32 v87, s22, 14, v179
	s_add_i32 s23, s23, 0
	s_waitcnt vmcnt(0)
	ds_write_b128 v87, v[152:155]
	ds_write_b128 v87, v[148:151] offset:8192
	v_add_u32_e32 v87, s23, v175
	ds_write_b128 v87, v[160:163] offset:49152
	ds_write_b128 v87, v[156:159] offset:57344
	v_lshl_add_u32 v87, s22, 13, v180
	ds_write_b128 v87, v[164:167] offset:32768

; __device__ __forceinline__ int crow(int r, int hi) { return (r & 3) + 8 * (r >> 2) + 4 * hi; }
; #define SLOAD(t) do { const int so_ = (t) * (KVBLK * 256); \
;         st_k0 = BLD(srdK, gofk, so_); st_k1 = BLD(srdK, gofk, so_ + 8192); st_v0 = BLD(srdV, gofk, so_); st_v1 = BLD(srdV, gofk, so_ + 8192); st_r = BLD(srdR, gofr, (t) * (KVBLK * 128)); } while (0)
; #define SWRITE(ts, v3) do { const int kb_ = ((ts) & 1) * SHM_K, rb_ = ((ts) & 1) * SHM_R, vb_ = (v3) * SHM_V; \
;         *(LAS bf16x8*)(lds + kb_ + kws) = st_k0; *(LAS bf16x8*)(lds + kb_ + kws + 32 * 256) = st_k1; \
;         *(LAS bf16x8*)(lds + vb_ + vst0) = st_v0; *(LAS bf16x8*)(lds + vb_ + vst1) = st_v1; *(LAS bf16x8*)(lds + rb_ + rws) = st_r; } while (0)
; __device__ __forceinline__ void attn_block(const Ptrs& P, int b, int h, int qb, LAS char* lds) {
;     ...
;         l_reg = l_reg * alpha + ps;
;         PK4(p0, 0, pa0); PK4(p0, 8, pa1); PK4(p1, 0, pa2); PK4(p1, 8, pa3);
;         if (__any(alpha < 1.f)) { if (hi == 0) al_l[r32] = alpha; asm volatile("s_waitcnt lgkmcnt(0)" ::: "memory");
; #pragma unroll
;             for (int d_ = 0; d_ < 4; ++d_)
; #pragma unroll
;                 for (int r = 0; r < 16; ++r) o[d_][r] *= al_l[crow(r, hi)]; }
;         if (ts < NT) SWRITE(ts, ts3);
;         if (ts + 1 < NT) SLOAD(ts + 1);
;         ++ts; ts3 = ts3 == 2 ? 0 : ts3 + 1;
;         __syncthreads();
.LBB0_627:
	s_add_i32 s22, s83, 1
	s_cmp_lg_u32 s83, 2
	s_cselect_b32 s39, s22, 0
	s_and_b64 s[22:23], exec, s[56:57]
	s_cselect_b32 s83, s83, s39
	s_add_i32 s22, s38, 1
	s_cmp_lg_u32 s38, 2
	s_cselect_b32 s38, s22, 0
	s_sub_i32 s81, s81, 64
	s_addk_i32 s78, 0x2000
	s_addk_i32 s79, 0x4000
	s_add_i32 s22, s80, s81
	s_add_i32 s82, s82, 64
	s_add_i32 s77, s77, 1
	v_add_f32_e32 v198, v198, v85
	v_xor_b32_e32 v3, 0x4000, v3
	v_xor_b32_e32 v197, 0x2000, v197
	s_cmp_eq_u32 s22, 0
	s_waitcnt lgkmcnt(0)
	s_barrier
	s_cbranch_scc1 .LBB0_629
	s_branch .LBB0_615
